# waves 4-7: whole qk epilogue after the step-4 barrier (overlaps the solve); their record emission moved into the single-wave T21 slot after the step-5 barrier
# speedup vs baseline: 1.0115x; 1.0115x over previous
.LBB0_206:
.LBB0_213:
	s_or_b64 exec, exec, s[28:29]
	s_and_b64 vcc, exec, s[94:95]
	v_mov_b32_e32 v101, v88
	v_mov_b32_e32 v102, v89
	v_mov_b32_e32 v103, v91
	v_mov_b32_e32 v104, v90
	s_cbranch_vccz .LBB0_215
	v_add_f32_e32 v3, v98, v100
	v_max_f32_e32 v4, 0, v3
	v_mul_f32_e64 v3, |v3|, s96
	v_exp_f32_e32 v3, v3
	v_and_b32_e32 v6, 64, v232
	v_add_u32_e32 v7, -1, v232
	v_cmp_lt_i32_e32 vcc, v7, v6
	v_add_f32_e32 v3, 1.0, v3
	v_log_f32_e32 v3, v3
	v_cndmask_b32_e32 v7, v7, v232, vcc
	v_lshlrev_b32_e32 v7, 2, v7
	v_readlane_b32 s6, v254, 27
	v_fmac_f32_e32 v4, 0x3f317218, v3
	v_mul_f32_e32 v3, 0x3fb8aa3b, v97
	v_exp_f32_e32 v3, v3
	v_readlane_b32 s7, v254, 28
	v_mul_f32_e32 v2, 0xbfb8aa3b, v99
	v_exp_f32_e32 v2, v2
	v_mul_f32_e64 v5, v4, -v3
	ds_bpermute_b32 v7, v7, v5
	v_add_f32_e32 v2, 1.0, v2
	v_rcp_f32_e32 v102, v2
	v_lshl_or_b32 v2, v232, 2, v229
	s_waitcnt lgkmcnt(0)
	v_fma_f32 v3, v4, -v3, v7
	v_add_u32_e32 v4, -2, v232
	v_cmp_lt_i32_e32 vcc, v4, v6
	v_cndmask_b32_e64 v3, v3, v5, s[6:7]
	v_readlane_b32 s6, v254, 29
	v_cndmask_b32_e32 v4, v4, v232, vcc
	v_lshlrev_b32_e32 v4, 2, v4
	ds_bpermute_b32 v4, v4, v3
	v_readlane_b32 s7, v254, 30
	s_waitcnt lgkmcnt(0)
	v_add_f32_e32 v4, v3, v4
	v_cndmask_b32_e64 v3, v4, v3, s[6:7]
	v_add_u32_e32 v4, -4, v232
	v_cmp_lt_i32_e32 vcc, v4, v6
	v_readlane_b32 s6, v254, 31
	v_readlane_b32 s7, v254, 32
	v_cndmask_b32_e32 v4, v4, v232, vcc
	v_lshlrev_b32_e32 v4, 2, v4
	ds_bpermute_b32 v4, v4, v3
	s_waitcnt lgkmcnt(0)
	v_add_f32_e32 v4, v3, v4
	v_cndmask_b32_e64 v3, v4, v3, s[6:7]
	v_add_u32_e32 v4, -8, v232
	v_cmp_lt_i32_e32 vcc, v4, v6
	v_readlane_b32 s6, v254, 33
	v_readlane_b32 s7, v254, 34
	v_cndmask_b32_e32 v4, v4, v232, vcc
	v_lshlrev_b32_e32 v4, 2, v4
	ds_bpermute_b32 v4, v4, v3
	s_waitcnt lgkmcnt(0)
	v_add_f32_e32 v4, v3, v4
	v_cndmask_b32_e64 v3, v4, v3, s[6:7]
	v_add_u32_e32 v4, -16, v232
	v_cmp_lt_i32_e32 vcc, v4, v6
	v_readlane_b32 s6, v254, 35
	v_readlane_b32 s7, v254, 36
	v_cndmask_b32_e32 v4, v4, v232, vcc
	v_lshlrev_b32_e32 v4, 2, v4
	ds_bpermute_b32 v4, v4, v3
	s_waitcnt lgkmcnt(0)
	v_add_f32_e32 v4, v3, v4
	v_cndmask_b32_e64 v3, v4, v3, s[6:7]
	v_subrev_u32_e32 v4, 32, v232
	v_cmp_lt_i32_e32 vcc, v4, v6
	v_readlane_b32 s6, v254, 37
	v_readlane_b32 s7, v254, 38
	v_cndmask_b32_e32 v4, v4, v232, vcc
	v_lshlrev_b32_e32 v4, 2, v4
	ds_bpermute_b32 v4, v4, v3
	s_waitcnt lgkmcnt(0)
	v_add_f32_e32 v4, v3, v4
	v_cndmask_b32_e64 v101, v4, v3, s[6:7]
	ds_bpermute_b32 v2, v2, v101
	v_mul_f32_e32 v3, 0x3fb8aa3b, v101
	v_exp_f32_e32 v103, v3
	s_waitcnt lgkmcnt(0)
	v_sub_f32_e32 v2, v2, v101
	v_mul_f32_e32 v2, 0x3fb8aa3b, v2
	v_exp_f32_e32 v104, v2

.LBB0_236:
	v_lshlrev_b32_e32 v88, 3, v95
	s_cmp_eq_u32 s48, 0
	v_or_b32_e32 v89, 16, v88
	s_waitcnt lgkmcnt(0)
	s_barrier
	s_cbranch_scc1 .LBB0_245
	s_cmp_gt_u32 s48, 3
	s_cbranch_scc0 .Lem_skip
	s_add_i32 s6, s48, -4
	v_lshlrev_b32_e32 v2, 9, v94
	v_lshlrev_b32_e32 v3, 2, v94
	v_lshlrev_b32_e32 v4, 11, v95
	v_lshlrev_b32_e32 v8, 4, v95
	s_lshl_b32 s7, s6, 6
	v_lshl_add_u32 v2, v95, 4, v2
	v_add_u32_e32 v3, 0x24b00, v3
	v_lshl_add_u32 v4, v94, 2, v4
	v_add_u32_e32 v8, s7, v8
	v_add_u32_e32 v2, s7, v2
	s_lshl_b32 s7, s6, 13
	s_add_i32 s7, s7, 0x8000
	v_add_u32_e32 v8, 0x24c00, v8
	v_add_u32_e32 v4, s7, v4
	s_lshl_b32 s7, s6, 10
	s_add_i32 s7, s7, s51
	v_add_u32_e32 v5, 0x80, v4
	v_lshl_add_u32 v9, v93, 4, s7
	ds_read_b32 v182, v3
	ds_read_b32 v184, v3 offset:128
	ds_read_b128 v[150:153], v2
	ds_read_b128 v[154:157], v2 offset:32
	ds_read_b128 v[158:161], v2 offset:256
	ds_read_b128 v[162:165], v2 offset:288
	ds_read_b128 v[166:169], v2 offset:16384
	ds_read_b128 v[170:173], v2 offset:16416
	ds_read_b128 v[174:177], v2 offset:16640
	ds_read_b128 v[178:181], v2 offset:16672
	ds_read_b128 v[186:189], v8
	ds_read_b128 v[190:193], v8 offset:32
	s_waitcnt lgkmcnt(2)
	ds_read2st64_b32 v[194:195], v4 offset1:2
	ds_read2st64_b32 v[196:197], v4 offset0:4 offset1:6
	ds_read2st64_b32 v[198:199], v4 offset0:16 offset1:18
	ds_read2st64_b32 v[200:201], v4 offset0:20 offset1:22
	ds_read2st64_b32 v[202:203], v5 offset1:2
	ds_read2st64_b32 v[204:205], v5 offset0:4 offset1:6
	ds_read2st64_b32 v[206:207], v5 offset0:16 offset1:18
	ds_read2st64_b32 v[208:209], v5 offset0:20 offset1:22
	v_pk_mul_f32 v[150:151], v[150:151], v[182:183] op_sel_hi:[1,0]
	v_pk_mul_f32 v[152:153], v[152:153], v[182:183] op_sel_hi:[1,0]
	v_pk_mul_f32 v[154:155], v[154:155], v[182:183] op_sel_hi:[1,0]
	v_pk_mul_f32 v[156:157], v[156:157], v[182:183] op_sel_hi:[1,0]
	v_cvt_pk_bf16_f32 v10, v150, v151
	v_cvt_pk_bf16_f32 v11, v152, v153
	v_cvt_pk_bf16_f32 v12, v154, v155
	v_cvt_pk_bf16_f32 v13, v156, v157
	v_add_u32_e32 v6, 0x4000, v9
	buffer_store_dwordx4 v[10:13], v6, s[72:75], 0 offen sc1
	v_pk_mul_f32 v[158:159], v[158:159], v[182:183] op_sel_hi:[1,0]
	v_pk_mul_f32 v[160:161], v[160:161], v[182:183] op_sel_hi:[1,0]
	v_pk_mul_f32 v[162:163], v[162:163], v[182:183] op_sel_hi:[1,0]
	v_pk_mul_f32 v[164:165], v[164:165], v[182:183] op_sel_hi:[1,0]
	v_cvt_pk_bf16_f32 v14, v158, v159
	v_cvt_pk_bf16_f32 v15, v160, v161
	v_cvt_pk_bf16_f32 v16, v162, v163
	v_cvt_pk_bf16_f32 v17, v164, v165
	v_add_u32_e32 v7, 0x5000, v9
	buffer_store_dwordx4 v[14:17], v7, s[72:75], 0 offen sc1
	v_pk_mul_f32 v[166:167], v[166:167], v[184:185] op_sel_hi:[1,0]
	v_pk_mul_f32 v[168:169], v[168:169], v[184:185] op_sel_hi:[1,0]
	v_pk_mul_f32 v[170:171], v[170:171], v[184:185] op_sel_hi:[1,0]
	v_pk_mul_f32 v[172:173], v[172:173], v[184:185] op_sel_hi:[1,0]
	v_cvt_pk_bf16_f32 v18, v166, v167
	v_cvt_pk_bf16_f32 v19, v168, v169
	v_cvt_pk_bf16_f32 v20, v170, v171
	v_cvt_pk_bf16_f32 v21, v172, v173
	v_add_u32_e32 v6, 0x6000, v9
	buffer_store_dwordx4 v[18:21], v6, s[72:75], 0 offen sc1
	v_pk_mul_f32 v[174:175], v[174:175], v[184:185] op_sel_hi:[1,0]
	v_pk_mul_f32 v[176:177], v[176:177], v[184:185] op_sel_hi:[1,0]
	v_pk_mul_f32 v[178:179], v[178:179], v[184:185] op_sel_hi:[1,0]
	v_pk_mul_f32 v[180:181], v[180:181], v[184:185] op_sel_hi:[1,0]
	v_cvt_pk_bf16_f32 v26, v174, v175
	v_cvt_pk_bf16_f32 v27, v176, v177
	v_cvt_pk_bf16_f32 v28, v178, v179
	v_cvt_pk_bf16_f32 v29, v180, v181
	v_add_u32_e32 v7, 0x7000, v9
	buffer_store_dwordx4 v[26:29], v7, s[72:75], 0 offen sc1
	s_waitcnt lgkmcnt(4)
	ds_read2st64_b32 v[210:211], v4 offset0:1 offset1:3
	ds_read2st64_b32 v[212:213], v4 offset0:5 offset1:7
	ds_read2st64_b32 v[214:215], v4 offset0:17 offset1:19
	ds_read2st64_b32 v[216:217], v4 offset0:21 offset1:23
	ds_read2st64_b32 v[106:107], v5 offset0:1 offset1:3
	ds_read2st64_b32 v[108:109], v5 offset0:5 offset1:7
	ds_read2st64_b32 v[110:111], v5 offset0:17 offset1:19
	ds_read2st64_b32 v[112:113], v5 offset0:21 offset1:23
	v_pk_mul_f32 v[194:195], v[194:195], v[186:187]
	v_pk_mul_f32 v[196:197], v[196:197], v[188:189]
	v_pk_mul_f32 v[198:199], v[198:199], v[190:191]
	v_pk_mul_f32 v[200:201], v[200:201], v[192:193]
	v_cvt_pk_bf16_f32 v30, v194, v195
	v_cvt_pk_bf16_f32 v31, v196, v197
	v_cvt_pk_bf16_f32 v32, v198, v199
	v_cvt_pk_bf16_f32 v33, v200, v201
	v_add_u32_e32 v6, 0xa000, v9
	buffer_store_dwordx4 v[30:33], v6, s[72:75], 0 offen sc1
	s_waitcnt lgkmcnt(8)
	v_pk_mul_f32 v[202:203], v[202:203], v[186:187]
	v_pk_mul_f32 v[204:205], v[204:205], v[188:189]
	v_pk_mul_f32 v[206:207], v[206:207], v[190:191]
	v_pk_mul_f32 v[208:209], v[208:209], v[192:193]
	v_cvt_pk_bf16_f32 v114, v202, v203
	v_cvt_pk_bf16_f32 v115, v204, v205
	v_cvt_pk_bf16_f32 v116, v206, v207
	v_cvt_pk_bf16_f32 v117, v208, v209
	v_add_u32_e32 v7, 0xb000, v9
	buffer_store_dwordx4 v[114:117], v7, s[72:75], 0 offen sc1
	s_waitcnt lgkmcnt(4)
	v_pk_mul_f32 v[210:211], v[210:211], v[186:187]
	v_pk_mul_f32 v[212:213], v[212:213], v[188:189]
	v_pk_mul_f32 v[214:215], v[214:215], v[190:191]
	v_pk_mul_f32 v[216:217], v[216:217], v[192:193]
	v_cvt_pk_bf16_f32 v118, v210, v211
	v_cvt_pk_bf16_f32 v119, v212, v213
	v_cvt_pk_bf16_f32 v120, v214, v215
	v_cvt_pk_bf16_f32 v121, v216, v217
	v_add_u32_e32 v6, 0xc000, v9
	buffer_store_dwordx4 v[118:121], v6, s[72:75], 0 offen sc1
	s_waitcnt lgkmcnt(0)
	v_pk_mul_f32 v[106:107], v[106:107], v[186:187]
	v_pk_mul_f32 v[108:109], v[108:109], v[188:189]
	v_pk_mul_f32 v[110:111], v[110:111], v[190:191]
	v_pk_mul_f32 v[112:113], v[112:113], v[192:193]
	v_cvt_pk_bf16_f32 v122, v106, v107
	v_cvt_pk_bf16_f32 v123, v108, v109
	v_cvt_pk_bf16_f32 v124, v110, v111
	v_cvt_pk_bf16_f32 v125, v112, v113
	v_add_u32_e32 v7, 0xd000, v9
	buffer_store_dwordx4 v[122:125], v7, s[72:75], 0 offen sc1
.Lem_skip:
	v_or_b32_e32 v18, 16, v88
	s_cbranch_execnz .LBB0_239
